# stack10 variant: mrun attention variant issues its 4 DMA pieces in the QK MFMA shadows (temps v198-201) instead of before the -m init
# speedup vs baseline: 1.0152x; 1.0023x over previous
.Lat_qk:
	s_mov_b64 vcc, s[36:37]
	s_cbranch_vccz .LBB1_532
	v_mov_b32_e32 v65, v64
	v_pk_mov_b32 v[66:67], v[64:65], v[64:65]
	v_pk_mov_b32 v[68:69], v[64:65], v[64:65]
	v_pk_mov_b32 v[70:71], v[64:65], v[64:65]
	v_pk_mov_b32 v[72:73], v[64:65], v[64:65]
	v_pk_mov_b32 v[74:75], v[64:65], v[64:65]
	v_pk_mov_b32 v[76:77], v[64:65], v[64:65]
	v_pk_mov_b32 v[78:79], v[64:65], v[64:65]
	s_waitcnt lgkmcnt(7)
	v_mfma_f32_32x32x16_bf16 v[80:95], v[166:169], v[126:129], v[64:79]
	s_waitcnt lgkmcnt(6)
	v_mfma_f32_32x32x16_bf16 v[96:111], v[174:177], v[126:129], v[64:79]
	s_lshl_b32 s25, s10, 15
	s_add_i32 s30, s25, s7
	s_mov_b32 s31, m0
	s_mov_b32 m0, s30
	s_nop 0
	global_load_lds_dwordx4 v[212:213], off
	s_mov_b32 m0, s31
	s_waitcnt lgkmcnt(5)
	v_mfma_f32_32x32x16_bf16 v[80:95], v[170:173], v[122:125], v[80:95]
	s_waitcnt lgkmcnt(4)
	v_mfma_f32_32x32x16_bf16 v[96:111], v[162:165], v[122:125], v[96:111]
	s_addk_i32 s30, 0x2000
	v_lshl_add_u64 v[198:199], v[212:213], 0, s[48:49]
	s_mov_b32 s31, m0
	s_mov_b32 m0, s30
	s_nop 0
	global_load_lds_dwordx4 v[198:199], off
	s_mov_b32 m0, s31
	s_waitcnt lgkmcnt(3)
	v_mfma_f32_32x32x16_bf16 v[80:95], v[158:161], v[118:121], v[80:95]
	s_waitcnt lgkmcnt(2)
	v_mfma_f32_32x32x16_bf16 v[96:111], v[154:157], v[118:121], v[96:111]
	v_lshl_add_u64 v[200:201], v[210:211], 0, s[26:27]
	s_add_i32 s25, s25, s9
	s_mov_b32 s30, m0
	s_mov_b32 m0, s25
	s_nop 0
	global_load_lds_dwordx4 v[200:201], off
	s_mov_b32 m0, s30
	s_waitcnt lgkmcnt(1)
	v_mfma_f32_32x32x16_bf16 v[80:95], v[150:153], v[114:117], v[80:95]
	s_waitcnt lgkmcnt(0)
	v_mfma_f32_32x32x16_bf16 v[96:111], v[146:149], v[114:117], v[96:111]
	s_addk_i32 s25, 0x2000
	s_mov_b64 s[30:31], 0x88000
	v_lshl_add_u64 v[198:199], v[200:201], 0, s[30:31]
	s_mov_b32 s30, m0
	s_mov_b32 m0, s25
	s_nop 0
	global_load_lds_dwordx4 v[198:199], off
	s_mov_b32 m0, s30
	s_lshl_b32 s25, s11, 15
	s_cbranch_execnz .LBB1_525
